# SSD item: wave roles of the second head swapped (tid bit 6 flipped for tid>=256) so each SIMD hosts one heavy (lt=1) and one light (lt=0) wave
# speedup vs baseline: 1.0079x; 1.0049x over previous
; DI int opaque_tid() { int t = threadIdx.x; asm volatile("" : "+v"(t)); return t; }
; DI void ssd_pair_item(const Params& P, unsigned char* smem, int b, int hp) {
;     const int tid0 = opaque_tid();
;     const int hd = 2 * hp + (tid0 >> 8), g = hp >> 2;
;     const float Aneg = -__expf(P.a_log[hd]), dtb = P.dt_bias[hd], Dsk = P.d_skip[hd];
;     const bf16_t* pbase = P_proj + (size_t)b * TT * LDP;
;     unsigned char* hb = smem + S2_HALF0 + (tid0 >> 8) * S2_HSTRIDE;
;     float* cum = (float*)(hb + S2_CUM); float* wsc = (float*)(hb + S2_WSC); float* dtv = (float*)(hb + S2_DTV); float* wcv = (float*)(hb + S2_WCV);
;     ...
;     __syncthreads();
;     for (int i = (tid0 & 255); i < 5 * 64; i += 256) { const int k = i >> 6, c = i & 63; const int ch = hd * 64 + c; wcv[i] = (k < 4) ? P.conv_w[k * 3072 + ch] : P.conv_b[ch]; }
.LBB0_275:
	s_andn2_b64 vcc, exec, s[2:3]
	s_cbranch_vccnz .LBB0_236
	v_lshrrev_b32_e32 v188, 2, v215
	v_and_b32_e32 v188, 64, v188
	v_xor_b32_e32 v188, v215, v188
	s_and_b32 s33, s96, 15
	s_and_b32 s0, s95, 15
	v_ashrrev_i32_e32 v4, 8, v188
	v_lshl_add_u32 v154, s33, 1, v4
	v_ashrrev_i32_e32 v155, 31, v154
	v_lshlrev_b64 v[0:1], 2, v[154:155]
	v_lshl_add_u64 v[2:3], s[24:25], 0, v[0:1]
	global_load_dword v6, v[2:3], off
	v_lshl_add_u64 v[2:3], s[22:23], 0, v[0:1]
	v_lshl_add_u64 v[0:1], s[26:27], 0, v[0:1]
	global_load_dword v189, v[2:3], off
	global_load_dword v156, v[0:1], off
	v_mul_i32_i24_e32 v190, 0xb800, v4
	v_and_b32_e32 v8, 0xff, v188
	v_lshl_or_b32 v2, v8, 2, v190
	v_add_u32_e32 v9, s88, v2
	v_bfe_u32 v2, v188, 6, 2
	s_lshl_b32 s0, s0, 7
	v_mul_u32_u24_e32 v2, 0xc00, v2
	v_lshlrev_b32_e32 v3, 6, v4
	v_lshlrev_b32_e32 v158, 6, v154
	v_and_b32_e32 v7, 63, v188
	v_add3_u32 v2, v2, s0, v3
	v_or_b32_e32 v0, v158, v7
	v_or_b32_e32 v2, v2, v7
	v_ashrrev_i32_e32 v1, 31, v0
	v_ashrrev_i32_e32 v3, 31, v2
	v_lshl_add_u64 v[0:1], v[0:1], 2, s[20:21]
	v_lshl_add_u64 v[2:3], v[2:3], 2, s[18:19]
	s_mov_b64 s[2:3], 0
	s_barrier
	s_branch .LBB0_278
